# v16 + scan chunk body v2: c1 term applied once per chunk via a per-lane collector of the reduced dot product; 6 LDS reads per step instead of 7
# baseline (speedup 1.0000x reference)
; #define PG8_LAS __attribute__((address_space(3)))
; __device__ __forceinline__ bf16_t f2bf(float f) { unsigned u = __float_as_uint(f); u += 0x7FFFu + ((u >> 16) & 1u); return (bf16_t)(u >> 16); }
; #define RW_WAIT(P, N) asm volatile("s_waitcnt lgkmcnt(" #N ")" : "+v"(P##w4), "+v"(P##kk4), "+v"(P##wr4), "+v"(P##ka4), "+v"(P##kp4), "+v"(P##v), "+v"(P##cc))
; #define RW_PAIR(ST) do { RW_LOAD(B, (ST) + 1); RW_WAIT(A, 7); RW_STEP(A, ST); RW_LOAD(A, (ST) + 2); RW_WAIT(B, 7); RW_STEP(B, (ST) + 1); } while (0)
; __device__ __forceinline__ void scans(int l, int s, unsigned char* shm) {
;     ...
;     if (wid < 4) {
;         const int loc = wid * 4 + (lane >> 4), col4 = (lane & 15) * 4;
;         float* RSp = B.RS + ((size_t)bhr * 64 + rbase + loc) * 64 + col4;
;         f32x2 S0 = {0.f, 0.f}, S1 = {0.f, 0.f};
;         if (s == 1) { const f32x4 t = *(const f32x4*)RSp; S0 = t.xy; S1 = t.zw; }
;         asm volatile("" : "+v"(S0), "+v"(S1));
;         __syncthreads();
; #pragma unroll 1
;         for (int cidx = 0; cidx < NCH; ++cidx) {
;             if (cidx > 0) { const int st = tid >> 4, r = tid & 15; Y[(size_t)(b_r * 2048 + (cidx - 1) * CS + st) * 512 + h_r * 64 + rbase + r] = f2bf(yl[((cidx - 1) & 1) * (CS * 16) + tid]); }
;             const float* bp = rbuf + (cidx & 1) * (CS * RST); float* ylw = yl + (cidx & 1) * (CS * 16);
;             const unsigned ab = (unsigned)(size_t)(PG8_LAS const float*)bp;
;             const unsigned a_col = ab + col4 * 4, a_row = ab + 1280 + loc * 4, a_cc = ab + 1344;
;             f32x4 Aw4, Akk4, Awr4, Aka4, Akp4, Bw4, Bkk4, Bwr4, Bka4, Bkp4; float Av, Bv; f32x2 Acc, Bcc;
;             float ykeep = 0.f;
;     ...
;             RW_LOAD(A, 0);
;             RW_PAIR(0); RW_PAIR(2); RW_PAIR(4); RW_PAIR(6); RW_PAIR(8); RW_PAIR(10); RW_PAIR(12);
;             RW_LOAD(B, 15); RW_WAIT(A, 7); RW_STEP(A, 14); RW_WAIT(B, 0); RW_STEP(B, 15);
.LBB0_757:
	s_add_u32 s18, s18, 0x1ac00000
	s_addc_u32 s19, s19, 0
	s_lshl_b32 s3, s29, 11
	s_lshl_b32 s2, s27, 6
	s_lshl_b32 s17, s27, 7
	v_lshlrev_b32_e32 v8, 2, v8
	v_lshlrev_b32_e32 v9, 6, v4
	s_add_u32 s20, s18, s17
	s_waitcnt vmcnt(3)
	v_add_u32_e32 v13, 0x500, v8
	v_add3_u32 v14, 0, v9, v8
	s_addc_u32 s21, s19, 0
	v_lshlrev_b32_e32 v8, 1, v4
	v_mov_b32_e32 v9, v177
	v_ashrrev_i32_e32 v12, 4, v48
	v_lshl_add_u64 v[8:9], s[20:21], 0, v[8:9]
	s_lshl_b32 s30, s16, 1
	v_lshl_add_u32 v5, v48, 2, 0
	v_lshl_add_u64 v[8:9], v[8:9], 0, s[30:31]
	s_mov_b32 s16, 0
	v_cmp_eq_u32_e64 s[40:41], 1, v4
	v_cmp_eq_u32_e64 s[42:43], 2, v4
	v_cmp_eq_u32_e64 s[44:45], 3, v4
	v_cmp_eq_u32_e64 s[46:47], 4, v4
	v_cmp_eq_u32_e64 s[48:49], 5, v4
	v_cmp_eq_u32_e64 s[50:51], 6, v4
	v_cmp_eq_u32_e64 s[52:53], 7, v4
	v_cmp_eq_u32_e64 s[54:55], 8, v4
	v_cmp_eq_u32_e64 s[56:57], 9, v4
	v_cmp_eq_u32_e64 s[58:59], 10, v4
	v_cmp_eq_u32_e64 s[60:61], 11, v4
	v_cmp_eq_u32_e64 s[62:63], 12, v4
	v_cmp_eq_u32_e64 s[64:65], 13, v4
	v_cmp_eq_u32_e64 s[66:67], 14, v4
	v_cmp_eq_u32_e64 s[68:69], 15, v4
	v_and_b32_e32 v11, 2, v4
	v_cmp_ne_u32_e64 s[100:101], 0, v11
	v_mul_u32_u24_e32 v125, 0x550, v4
	v_add3_u32 v10, v12, s3, -16
	s_movk_i32 s17, 0xff00
	s_waitcnt vmcnt(0)
	s_barrier
	s_branch .LBB0_759
.LBB0_758:
	s_and_b32 s20, s16, 1
	s_mul_i32 s21, s20, 0x5500
	v_add_u32_e32 v11, s21, v176
	v_add_u32_e32 v15, s21, v13
	s_addk_i32 s21, 0x540
	v_mov_b32_e32 v16, s21
	ds_read_b128 v[20:23], v11
	ds_read_b128 v[24:27], v11 offset:256
	ds_read_b128 v[28:31], v11 offset:512
	ds_read_b128 v[32:35], v11 offset:768
	ds_read_b128 v[36:39], v11 offset:1024
	ds_read_b32 v40, v15
	ds_read_b128 v[44:47], v11 offset:1360
	ds_read_b128 v[48:51], v11 offset:1616
	ds_read_b128 v[52:55], v11 offset:1872
	ds_read_b128 v[56:59], v11 offset:2128
	ds_read_b128 v[60:63], v11 offset:2384
	s_waitcnt lgkmcnt(5)
	v_pk_mul_f32 v[84:85], v[0:1], v[24:25]
	v_pk_fma_f32 v[84:85], v[2:3], v[26:27], v[84:85]
	v_add_f32_e32 v86, v84, v85
	v_pk_mul_f32 v[90:91], v[0:1], v[28:29]
	v_pk_fma_f32 v[90:91], v[2:3], v[30:31], v[90:91]
	v_add_f32_dpp v88, v86, v86 quad_perm:[1,0,3,2] row_mask:0xf bank_mask:0xf bound_ctrl:1
	v_pk_mul_f32 v[92:93], v[36:37], v[40:41] op_sel_hi:[1,0]
	v_pk_fma_f32 v[92:93], v[0:1], v[20:21], v[92:93]
	v_add_f32_dpp v88, v88, v88 quad_perm:[2,3,0,1] row_mask:0xf bank_mask:0xf bound_ctrl:1
	v_pk_mul_f32 v[94:95], v[38:39], v[40:41] op_sel_hi:[1,0]
	v_pk_fma_f32 v[94:95], v[2:3], v[22:23], v[94:95]
	v_add_f32_dpp v88, v88, v88 row_half_mirror row_mask:0xf bank_mask:0xf bound_ctrl:1
	v_add_f32_e32 v68, v90, v91
	ds_read_b32 v64, v15 offset:1360
	v_add_f32_dpp v88, v88, v88 row_mirror row_mask:0xf bank_mask:0xf bound_ctrl:1
	v_pk_fma_f32 v[0:1], v[32:33], v[88:89], v[92:93] op_sel_hi:[1,0,1] neg_lo:[0,1,0] neg_hi:[0,1,0]
	v_pk_fma_f32 v[2:3], v[34:35], v[88:89], v[94:95] op_sel_hi:[1,0,1] neg_lo:[0,1,0] neg_hi:[0,1,0]
	v_mov_b32_e32 v114, v88
	ds_read_b128 v[20:23], v11 offset:2720
	ds_read_b128 v[24:27], v11 offset:2976
	ds_read_b128 v[28:31], v11 offset:3232
	ds_read_b128 v[32:35], v11 offset:3488
	ds_read_b128 v[36:39], v11 offset:3744
	s_waitcnt lgkmcnt(5)
	v_pk_mul_f32 v[84:85], v[0:1], v[48:49]
	v_pk_fma_f32 v[84:85], v[2:3], v[50:51], v[84:85]
	v_add_f32_e32 v86, v84, v85
	v_pk_mul_f32 v[90:91], v[0:1], v[52:53]
	v_pk_fma_f32 v[90:91], v[2:3], v[54:55], v[90:91]
	v_add_f32_dpp v88, v86, v86 quad_perm:[1,0,3,2] row_mask:0xf bank_mask:0xf bound_ctrl:1
	v_pk_mul_f32 v[92:93], v[60:61], v[64:65] op_sel_hi:[1,0]
	v_pk_fma_f32 v[92:93], v[0:1], v[44:45], v[92:93]
	v_add_f32_dpp v88, v88, v88 quad_perm:[2,3,0,1] row_mask:0xf bank_mask:0xf bound_ctrl:1
	v_pk_mul_f32 v[94:95], v[62:63], v[64:65] op_sel_hi:[1,0]
	v_pk_fma_f32 v[94:95], v[2:3], v[46:47], v[94:95]
	v_add_f32_dpp v88, v88, v88 row_half_mirror row_mask:0xf bank_mask:0xf bound_ctrl:1
	v_add_f32_e32 v69, v90, v91
	ds_read_b32 v40, v15 offset:2720
	v_add_f32_dpp v88, v88, v88 row_mirror row_mask:0xf bank_mask:0xf bound_ctrl:1
	v_pk_fma_f32 v[0:1], v[56:57], v[88:89], v[92:93] op_sel_hi:[1,0,1] neg_lo:[0,1,0] neg_hi:[0,1,0]
	v_pk_fma_f32 v[2:3], v[58:59], v[88:89], v[94:95] op_sel_hi:[1,0,1] neg_lo:[0,1,0] neg_hi:[0,1,0]
	v_cndmask_b32_e64 v114, v114, v88, s[40:41]
	ds_read_b128 v[44:47], v11 offset:4080
	ds_read_b128 v[48:51], v11 offset:4336
	ds_read_b128 v[52:55], v11 offset:4592
	ds_read_b128 v[56:59], v11 offset:4848
	ds_read_b128 v[60:63], v11 offset:5104
	s_waitcnt lgkmcnt(5)
	v_pk_mul_f32 v[84:85], v[0:1], v[24:25]
	v_pk_fma_f32 v[84:85], v[2:3], v[26:27], v[84:85]
	v_add_f32_e32 v86, v84, v85
	v_pk_mul_f32 v[90:91], v[0:1], v[28:29]
	v_pk_fma_f32 v[90:91], v[2:3], v[30:31], v[90:91]
	v_add_f32_dpp v88, v86, v86 quad_perm:[1,0,3,2] row_mask:0xf bank_mask:0xf bound_ctrl:1
	v_pk_mul_f32 v[92:93], v[36:37], v[40:41] op_sel_hi:[1,0]
	v_pk_fma_f32 v[92:93], v[0:1], v[20:21], v[92:93]
	v_add_f32_dpp v88, v88, v88 quad_perm:[2,3,0,1] row_mask:0xf bank_mask:0xf bound_ctrl:1
	v_pk_mul_f32 v[94:95], v[38:39], v[40:41] op_sel_hi:[1,0]
	v_pk_fma_f32 v[94:95], v[2:3], v[22:23], v[94:95]
	v_add_f32_dpp v88, v88, v88 row_half_mirror row_mask:0xf bank_mask:0xf bound_ctrl:1
	v_add_f32_e32 v70, v90, v91
	ds_read_b32 v64, v15 offset:4080
	v_add_f32_dpp v88, v88, v88 row_mirror row_mask:0xf bank_mask:0xf bound_ctrl:1
	v_pk_fma_f32 v[0:1], v[32:33], v[88:89], v[92:93] op_sel_hi:[1,0,1] neg_lo:[0,1,0] neg_hi:[0,1,0]
	v_pk_fma_f32 v[2:3], v[34:35], v[88:89], v[94:95] op_sel_hi:[1,0,1] neg_lo:[0,1,0] neg_hi:[0,1,0]
	v_cndmask_b32_e64 v114, v114, v88, s[42:43]
	ds_read_b128 v[20:23], v11 offset:5440
	ds_read_b128 v[24:27], v11 offset:5696
	ds_read_b128 v[28:31], v11 offset:5952
	ds_read_b128 v[32:35], v11 offset:6208
	ds_read_b128 v[36:39], v11 offset:6464
	s_waitcnt lgkmcnt(5)
; #define RW_PAIR(ST) do { RW_LOAD(B, (ST) + 1); RW_WAIT(A, 7); RW_STEP(A, ST); RW_LOAD(A, (ST) + 2); RW_WAIT(B, 7); RW_STEP(B, (ST) + 1); } while (0)
; __device__ __forceinline__ void scans(int l, int s, unsigned char* shm) {
;     ...
;             RW_LOAD(A, 0);
;             RW_PAIR(0); RW_PAIR(2); RW_PAIR(4); RW_PAIR(6); RW_PAIR(8); RW_PAIR(10); RW_PAIR(12);
	v_pk_mul_f32 v[84:85], v[0:1], v[48:49]
	v_pk_fma_f32 v[84:85], v[2:3], v[50:51], v[84:85]
	v_add_f32_e32 v86, v84, v85
	v_pk_mul_f32 v[90:91], v[0:1], v[52:53]
	v_pk_fma_f32 v[90:91], v[2:3], v[54:55], v[90:91]
	v_add_f32_dpp v88, v86, v86 quad_perm:[1,0,3,2] row_mask:0xf bank_mask:0xf bound_ctrl:1
	v_pk_mul_f32 v[92:93], v[60:61], v[64:65] op_sel_hi:[1,0]
	v_pk_fma_f32 v[92:93], v[0:1], v[44:45], v[92:93]
	v_add_f32_dpp v88, v88, v88 quad_perm:[2,3,0,1] row_mask:0xf bank_mask:0xf bound_ctrl:1
	v_pk_mul_f32 v[94:95], v[62:63], v[64:65] op_sel_hi:[1,0]
	v_pk_fma_f32 v[94:95], v[2:3], v[46:47], v[94:95]
	v_add_f32_dpp v88, v88, v88 row_half_mirror row_mask:0xf bank_mask:0xf bound_ctrl:1
	v_add_f32_e32 v71, v90, v91
	ds_read_b32 v40, v15 offset:5440
	v_add_f32_dpp v88, v88, v88 row_mirror row_mask:0xf bank_mask:0xf bound_ctrl:1
	v_pk_fma_f32 v[0:1], v[56:57], v[88:89], v[92:93] op_sel_hi:[1,0,1] neg_lo:[0,1,0] neg_hi:[0,1,0]
	v_pk_fma_f32 v[2:3], v[58:59], v[88:89], v[94:95] op_sel_hi:[1,0,1] neg_lo:[0,1,0] neg_hi:[0,1,0]
	v_cndmask_b32_e64 v114, v114, v88, s[44:45]
	ds_read_b128 v[44:47], v11 offset:6800
	ds_read_b128 v[48:51], v11 offset:7056
	ds_read_b128 v[52:55], v11 offset:7312
	ds_read_b128 v[56:59], v11 offset:7568
	ds_read_b128 v[60:63], v11 offset:7824
	s_waitcnt lgkmcnt(5)
	v_pk_mul_f32 v[84:85], v[0:1], v[24:25]
	v_pk_fma_f32 v[84:85], v[2:3], v[26:27], v[84:85]
	v_add_f32_e32 v86, v84, v85
	v_pk_mul_f32 v[90:91], v[0:1], v[28:29]
	v_pk_fma_f32 v[90:91], v[2:3], v[30:31], v[90:91]
	v_add_f32_dpp v88, v86, v86 quad_perm:[1,0,3,2] row_mask:0xf bank_mask:0xf bound_ctrl:1
	v_pk_mul_f32 v[92:93], v[36:37], v[40:41] op_sel_hi:[1,0]
	v_pk_fma_f32 v[92:93], v[0:1], v[20:21], v[92:93]
	v_add_f32_dpp v88, v88, v88 quad_perm:[2,3,0,1] row_mask:0xf bank_mask:0xf bound_ctrl:1
	v_pk_mul_f32 v[94:95], v[38:39], v[40:41] op_sel_hi:[1,0]
	v_pk_fma_f32 v[94:95], v[2:3], v[22:23], v[94:95]
	v_add_f32_dpp v88, v88, v88 row_half_mirror row_mask:0xf bank_mask:0xf bound_ctrl:1
	v_add_f32_e32 v72, v90, v91
	ds_read_b32 v64, v15 offset:6800
	v_add_f32_dpp v88, v88, v88 row_mirror row_mask:0xf bank_mask:0xf bound_ctrl:1
	v_pk_fma_f32 v[0:1], v[32:33], v[88:89], v[92:93] op_sel_hi:[1,0,1] neg_lo:[0,1,0] neg_hi:[0,1,0]
	v_pk_fma_f32 v[2:3], v[34:35], v[88:89], v[94:95] op_sel_hi:[1,0,1] neg_lo:[0,1,0] neg_hi:[0,1,0]
	v_cndmask_b32_e64 v114, v114, v88, s[46:47]
	ds_read_b128 v[20:23], v11 offset:8160
	ds_read_b128 v[24:27], v11 offset:8416
	ds_read_b128 v[28:31], v11 offset:8672
	ds_read_b128 v[32:35], v11 offset:8928
	ds_read_b128 v[36:39], v11 offset:9184
	s_waitcnt lgkmcnt(5)
	v_pk_mul_f32 v[84:85], v[0:1], v[48:49]
	v_pk_fma_f32 v[84:85], v[2:3], v[50:51], v[84:85]
	v_add_f32_e32 v86, v84, v85
	v_pk_mul_f32 v[90:91], v[0:1], v[52:53]
	v_pk_fma_f32 v[90:91], v[2:3], v[54:55], v[90:91]
	v_add_f32_dpp v88, v86, v86 quad_perm:[1,0,3,2] row_mask:0xf bank_mask:0xf bound_ctrl:1
	v_pk_mul_f32 v[92:93], v[60:61], v[64:65] op_sel_hi:[1,0]
	v_pk_fma_f32 v[92:93], v[0:1], v[44:45], v[92:93]
	v_add_f32_dpp v88, v88, v88 quad_perm:[2,3,0,1] row_mask:0xf bank_mask:0xf bound_ctrl:1
	v_pk_mul_f32 v[94:95], v[62:63], v[64:65] op_sel_hi:[1,0]
	v_pk_fma_f32 v[94:95], v[2:3], v[46:47], v[94:95]
	v_add_f32_dpp v88, v88, v88 row_half_mirror row_mask:0xf bank_mask:0xf bound_ctrl:1
	v_add_f32_e32 v73, v90, v91
	ds_read_b32 v40, v15 offset:8160
	v_add_f32_dpp v88, v88, v88 row_mirror row_mask:0xf bank_mask:0xf bound_ctrl:1
	v_pk_fma_f32 v[0:1], v[56:57], v[88:89], v[92:93] op_sel_hi:[1,0,1] neg_lo:[0,1,0] neg_hi:[0,1,0]
	v_pk_fma_f32 v[2:3], v[58:59], v[88:89], v[94:95] op_sel_hi:[1,0,1] neg_lo:[0,1,0] neg_hi:[0,1,0]
	v_cndmask_b32_e64 v114, v114, v88, s[48:49]
	ds_read_b128 v[44:47], v11 offset:9520
	ds_read_b128 v[48:51], v11 offset:9776
	ds_read_b128 v[52:55], v11 offset:10032
	ds_read_b128 v[56:59], v11 offset:10288
	ds_read_b128 v[60:63], v11 offset:10544
	s_waitcnt lgkmcnt(5)
	v_pk_mul_f32 v[84:85], v[0:1], v[24:25]
	v_pk_fma_f32 v[84:85], v[2:3], v[26:27], v[84:85]
	v_add_f32_e32 v86, v84, v85
	v_pk_mul_f32 v[90:91], v[0:1], v[28:29]
	v_pk_fma_f32 v[90:91], v[2:3], v[30:31], v[90:91]
	v_add_f32_dpp v88, v86, v86 quad_perm:[1,0,3,2] row_mask:0xf bank_mask:0xf bound_ctrl:1
	v_pk_mul_f32 v[92:93], v[36:37], v[40:41] op_sel_hi:[1,0]
	v_pk_fma_f32 v[92:93], v[0:1], v[20:21], v[92:93]
	v_add_f32_dpp v88, v88, v88 quad_perm:[2,3,0,1] row_mask:0xf bank_mask:0xf bound_ctrl:1
	v_pk_mul_f32 v[94:95], v[38:39], v[40:41] op_sel_hi:[1,0]
	v_pk_fma_f32 v[94:95], v[2:3], v[22:23], v[94:95]
	v_add_f32_dpp v88, v88, v88 row_half_mirror row_mask:0xf bank_mask:0xf bound_ctrl:1
	v_add_f32_e32 v74, v90, v91
	ds_read_b32 v64, v15 offset:9520
	v_add_f32_dpp v88, v88, v88 row_mirror row_mask:0xf bank_mask:0xf bound_ctrl:1
	v_pk_fma_f32 v[0:1], v[32:33], v[88:89], v[92:93] op_sel_hi:[1,0,1] neg_lo:[0,1,0] neg_hi:[0,1,0]
	v_pk_fma_f32 v[2:3], v[34:35], v[88:89], v[94:95] op_sel_hi:[1,0,1] neg_lo:[0,1,0] neg_hi:[0,1,0]
	v_cndmask_b32_e64 v114, v114, v88, s[50:51]
	ds_read_b128 v[20:23], v11 offset:10880
	ds_read_b128 v[24:27], v11 offset:11136
	ds_read_b128 v[28:31], v11 offset:11392
	ds_read_b128 v[32:35], v11 offset:11648
	ds_read_b128 v[36:39], v11 offset:11904
	s_waitcnt lgkmcnt(5)
; #define RW_PAIR(ST) do { RW_LOAD(B, (ST) + 1); RW_WAIT(A, 7); RW_STEP(A, ST); RW_LOAD(A, (ST) + 2); RW_WAIT(B, 7); RW_STEP(B, (ST) + 1); } while (0)
; __device__ __forceinline__ void scans(int l, int s, unsigned char* shm) {
;     ...
;             RW_LOAD(A, 0);
;             RW_PAIR(0); RW_PAIR(2); RW_PAIR(4); RW_PAIR(6); RW_PAIR(8); RW_PAIR(10); RW_PAIR(12);
	v_pk_mul_f32 v[84:85], v[0:1], v[48:49]
	v_pk_fma_f32 v[84:85], v[2:3], v[50:51], v[84:85]
	v_add_f32_e32 v86, v84, v85
	v_pk_mul_f32 v[90:91], v[0:1], v[52:53]
	v_pk_fma_f32 v[90:91], v[2:3], v[54:55], v[90:91]
	v_add_f32_dpp v88, v86, v86 quad_perm:[1,0,3,2] row_mask:0xf bank_mask:0xf bound_ctrl:1
	v_pk_mul_f32 v[92:93], v[60:61], v[64:65] op_sel_hi:[1,0]
	v_pk_fma_f32 v[92:93], v[0:1], v[44:45], v[92:93]
	v_add_f32_dpp v88, v88, v88 quad_perm:[2,3,0,1] row_mask:0xf bank_mask:0xf bound_ctrl:1
	v_pk_mul_f32 v[94:95], v[62:63], v[64:65] op_sel_hi:[1,0]
	v_pk_fma_f32 v[94:95], v[2:3], v[46:47], v[94:95]
	v_add_f32_dpp v88, v88, v88 row_half_mirror row_mask:0xf bank_mask:0xf bound_ctrl:1
	v_add_f32_e32 v75, v90, v91
	ds_read_b32 v40, v15 offset:10880
	v_add_f32_dpp v88, v88, v88 row_mirror row_mask:0xf bank_mask:0xf bound_ctrl:1
	v_pk_fma_f32 v[0:1], v[56:57], v[88:89], v[92:93] op_sel_hi:[1,0,1] neg_lo:[0,1,0] neg_hi:[0,1,0]
	v_pk_fma_f32 v[2:3], v[58:59], v[88:89], v[94:95] op_sel_hi:[1,0,1] neg_lo:[0,1,0] neg_hi:[0,1,0]
	v_cndmask_b32_e64 v114, v114, v88, s[52:53]
	ds_read_b128 v[44:47], v11 offset:12240
	ds_read_b128 v[48:51], v11 offset:12496
	ds_read_b128 v[52:55], v11 offset:12752
	ds_read_b128 v[56:59], v11 offset:13008
	ds_read_b128 v[60:63], v11 offset:13264
	s_waitcnt lgkmcnt(5)
	v_pk_mul_f32 v[84:85], v[0:1], v[24:25]
	v_pk_fma_f32 v[84:85], v[2:3], v[26:27], v[84:85]
	v_add_f32_e32 v86, v84, v85
	v_pk_mul_f32 v[90:91], v[0:1], v[28:29]
	v_pk_fma_f32 v[90:91], v[2:3], v[30:31], v[90:91]
	v_add_f32_dpp v88, v86, v86 quad_perm:[1,0,3,2] row_mask:0xf bank_mask:0xf bound_ctrl:1
	v_pk_mul_f32 v[92:93], v[36:37], v[40:41] op_sel_hi:[1,0]
	v_pk_fma_f32 v[92:93], v[0:1], v[20:21], v[92:93]
	v_add_f32_dpp v88, v88, v88 quad_perm:[2,3,0,1] row_mask:0xf bank_mask:0xf bound_ctrl:1
	v_pk_mul_f32 v[94:95], v[38:39], v[40:41] op_sel_hi:[1,0]
	v_pk_fma_f32 v[94:95], v[2:3], v[22:23], v[94:95]
	v_add_f32_dpp v88, v88, v88 row_half_mirror row_mask:0xf bank_mask:0xf bound_ctrl:1
	v_add_f32_e32 v76, v90, v91
	ds_read_b32 v64, v15 offset:12240
	v_add_f32_dpp v88, v88, v88 row_mirror row_mask:0xf bank_mask:0xf bound_ctrl:1
	v_pk_fma_f32 v[0:1], v[32:33], v[88:89], v[92:93] op_sel_hi:[1,0,1] neg_lo:[0,1,0] neg_hi:[0,1,0]
	v_pk_fma_f32 v[2:3], v[34:35], v[88:89], v[94:95] op_sel_hi:[1,0,1] neg_lo:[0,1,0] neg_hi:[0,1,0]
	v_cndmask_b32_e64 v114, v114, v88, s[54:55]
	ds_read_b128 v[20:23], v11 offset:13600
	ds_read_b128 v[24:27], v11 offset:13856
	ds_read_b128 v[28:31], v11 offset:14112
	ds_read_b128 v[32:35], v11 offset:14368
	ds_read_b128 v[36:39], v11 offset:14624
	s_waitcnt lgkmcnt(5)
	v_pk_mul_f32 v[84:85], v[0:1], v[48:49]
	v_pk_fma_f32 v[84:85], v[2:3], v[50:51], v[84:85]
	v_add_f32_e32 v86, v84, v85
	v_pk_mul_f32 v[90:91], v[0:1], v[52:53]
	v_pk_fma_f32 v[90:91], v[2:3], v[54:55], v[90:91]
	v_add_f32_dpp v88, v86, v86 quad_perm:[1,0,3,2] row_mask:0xf bank_mask:0xf bound_ctrl:1
	v_pk_mul_f32 v[92:93], v[60:61], v[64:65] op_sel_hi:[1,0]
	v_pk_fma_f32 v[92:93], v[0:1], v[44:45], v[92:93]
	v_add_f32_dpp v88, v88, v88 quad_perm:[2,3,0,1] row_mask:0xf bank_mask:0xf bound_ctrl:1
	v_pk_mul_f32 v[94:95], v[62:63], v[64:65] op_sel_hi:[1,0]
	v_pk_fma_f32 v[94:95], v[2:3], v[46:47], v[94:95]
	v_add_f32_dpp v88, v88, v88 row_half_mirror row_mask:0xf bank_mask:0xf bound_ctrl:1
	v_add_f32_e32 v77, v90, v91
	ds_read_b32 v40, v15 offset:13600
	v_add_f32_dpp v88, v88, v88 row_mirror row_mask:0xf bank_mask:0xf bound_ctrl:1
	v_pk_fma_f32 v[0:1], v[56:57], v[88:89], v[92:93] op_sel_hi:[1,0,1] neg_lo:[0,1,0] neg_hi:[0,1,0]
	v_pk_fma_f32 v[2:3], v[58:59], v[88:89], v[94:95] op_sel_hi:[1,0,1] neg_lo:[0,1,0] neg_hi:[0,1,0]
	v_cndmask_b32_e64 v114, v114, v88, s[56:57]
	ds_read_b128 v[44:47], v11 offset:14960
	ds_read_b128 v[48:51], v11 offset:15216
	ds_read_b128 v[52:55], v11 offset:15472
	ds_read_b128 v[56:59], v11 offset:15728
	ds_read_b128 v[60:63], v11 offset:15984
	s_waitcnt lgkmcnt(5)
	v_pk_mul_f32 v[84:85], v[0:1], v[24:25]
	v_pk_fma_f32 v[84:85], v[2:3], v[26:27], v[84:85]
	v_add_f32_e32 v86, v84, v85
	v_pk_mul_f32 v[90:91], v[0:1], v[28:29]
	v_pk_fma_f32 v[90:91], v[2:3], v[30:31], v[90:91]
	v_add_f32_dpp v88, v86, v86 quad_perm:[1,0,3,2] row_mask:0xf bank_mask:0xf bound_ctrl:1
	v_pk_mul_f32 v[92:93], v[36:37], v[40:41] op_sel_hi:[1,0]
	v_pk_fma_f32 v[92:93], v[0:1], v[20:21], v[92:93]
	v_add_f32_dpp v88, v88, v88 quad_perm:[2,3,0,1] row_mask:0xf bank_mask:0xf bound_ctrl:1
	v_pk_mul_f32 v[94:95], v[38:39], v[40:41] op_sel_hi:[1,0]
	v_pk_fma_f32 v[94:95], v[2:3], v[22:23], v[94:95]
	v_add_f32_dpp v88, v88, v88 row_half_mirror row_mask:0xf bank_mask:0xf bound_ctrl:1
	v_add_f32_e32 v78, v90, v91
	ds_read_b32 v64, v15 offset:14960
	v_add_f32_dpp v88, v88, v88 row_mirror row_mask:0xf bank_mask:0xf bound_ctrl:1
	v_pk_fma_f32 v[0:1], v[32:33], v[88:89], v[92:93] op_sel_hi:[1,0,1] neg_lo:[0,1,0] neg_hi:[0,1,0]
	v_pk_fma_f32 v[2:3], v[34:35], v[88:89], v[94:95] op_sel_hi:[1,0,1] neg_lo:[0,1,0] neg_hi:[0,1,0]
	v_cndmask_b32_e64 v114, v114, v88, s[58:59]
	ds_read_b128 v[20:23], v11 offset:16320
	ds_read_b128 v[24:27], v11 offset:16576
	ds_read_b128 v[28:31], v11 offset:16832
	ds_read_b128 v[32:35], v11 offset:17088
	ds_read_b128 v[36:39], v11 offset:17344
	s_waitcnt lgkmcnt(5)
; #define RW_PAIR(ST) do { RW_LOAD(B, (ST) + 1); RW_WAIT(A, 7); RW_STEP(A, ST); RW_LOAD(A, (ST) + 2); RW_WAIT(B, 7); RW_STEP(B, (ST) + 1); } while (0)
; __device__ __forceinline__ void scans(int l, int s, unsigned char* shm) {
;     ...
;             RW_LOAD(A, 0);
;             RW_PAIR(0); RW_PAIR(2); RW_PAIR(4); RW_PAIR(6); RW_PAIR(8); RW_PAIR(10); RW_PAIR(12);
	v_pk_mul_f32 v[84:85], v[0:1], v[48:49]
	v_pk_fma_f32 v[84:85], v[2:3], v[50:51], v[84:85]
	v_add_f32_e32 v86, v84, v85
	v_pk_mul_f32 v[90:91], v[0:1], v[52:53]
	v_pk_fma_f32 v[90:91], v[2:3], v[54:55], v[90:91]
	v_add_f32_dpp v88, v86, v86 quad_perm:[1,0,3,2] row_mask:0xf bank_mask:0xf bound_ctrl:1
	v_pk_mul_f32 v[92:93], v[60:61], v[64:65] op_sel_hi:[1,0]
	v_pk_fma_f32 v[92:93], v[0:1], v[44:45], v[92:93]
	v_add_f32_dpp v88, v88, v88 quad_perm:[2,3,0,1] row_mask:0xf bank_mask:0xf bound_ctrl:1
	v_pk_mul_f32 v[94:95], v[62:63], v[64:65] op_sel_hi:[1,0]
	v_pk_fma_f32 v[94:95], v[2:3], v[46:47], v[94:95]
	v_add_f32_dpp v88, v88, v88 row_half_mirror row_mask:0xf bank_mask:0xf bound_ctrl:1
	v_add_f32_e32 v79, v90, v91
	ds_read_b32 v40, v15 offset:16320
	v_add_f32_dpp v88, v88, v88 row_mirror row_mask:0xf bank_mask:0xf bound_ctrl:1
	v_pk_fma_f32 v[0:1], v[56:57], v[88:89], v[92:93] op_sel_hi:[1,0,1] neg_lo:[0,1,0] neg_hi:[0,1,0]
	v_pk_fma_f32 v[2:3], v[58:59], v[88:89], v[94:95] op_sel_hi:[1,0,1] neg_lo:[0,1,0] neg_hi:[0,1,0]
	v_cndmask_b32_e64 v114, v114, v88, s[60:61]
	ds_read_b128 v[44:47], v11 offset:17680
	ds_read_b128 v[48:51], v11 offset:17936
	ds_read_b128 v[52:55], v11 offset:18192
	ds_read_b128 v[56:59], v11 offset:18448
	ds_read_b128 v[60:63], v11 offset:18704
	s_waitcnt lgkmcnt(5)
	v_pk_mul_f32 v[84:85], v[0:1], v[24:25]
	v_pk_fma_f32 v[84:85], v[2:3], v[26:27], v[84:85]
	v_add_f32_e32 v86, v84, v85
	v_pk_mul_f32 v[90:91], v[0:1], v[28:29]
	v_pk_fma_f32 v[90:91], v[2:3], v[30:31], v[90:91]
	v_add_f32_dpp v88, v86, v86 quad_perm:[1,0,3,2] row_mask:0xf bank_mask:0xf bound_ctrl:1
	v_pk_mul_f32 v[92:93], v[36:37], v[40:41] op_sel_hi:[1,0]
	v_pk_fma_f32 v[92:93], v[0:1], v[20:21], v[92:93]
	v_add_f32_dpp v88, v88, v88 quad_perm:[2,3,0,1] row_mask:0xf bank_mask:0xf bound_ctrl:1
	v_pk_mul_f32 v[94:95], v[38:39], v[40:41] op_sel_hi:[1,0]
	v_pk_fma_f32 v[94:95], v[2:3], v[22:23], v[94:95]
	v_add_f32_dpp v88, v88, v88 row_half_mirror row_mask:0xf bank_mask:0xf bound_ctrl:1
	v_add_f32_e32 v80, v90, v91
	ds_read_b32 v64, v15 offset:17680
	v_add_f32_dpp v88, v88, v88 row_mirror row_mask:0xf bank_mask:0xf bound_ctrl:1
	v_pk_fma_f32 v[0:1], v[32:33], v[88:89], v[92:93] op_sel_hi:[1,0,1] neg_lo:[0,1,0] neg_hi:[0,1,0]
	v_pk_fma_f32 v[2:3], v[34:35], v[88:89], v[94:95] op_sel_hi:[1,0,1] neg_lo:[0,1,0] neg_hi:[0,1,0]
	v_cndmask_b32_e64 v114, v114, v88, s[62:63]
	ds_read_b128 v[20:23], v11 offset:19040
	ds_read_b128 v[24:27], v11 offset:19296
	ds_read_b128 v[28:31], v11 offset:19552
	ds_read_b128 v[32:35], v11 offset:19808
	ds_read_b128 v[36:39], v11 offset:20064
	s_waitcnt lgkmcnt(5)
	v_pk_mul_f32 v[84:85], v[0:1], v[48:49]
	v_pk_fma_f32 v[84:85], v[2:3], v[50:51], v[84:85]
	v_add_f32_e32 v86, v84, v85
	v_pk_mul_f32 v[90:91], v[0:1], v[52:53]
	v_pk_fma_f32 v[90:91], v[2:3], v[54:55], v[90:91]
	v_add_f32_dpp v88, v86, v86 quad_perm:[1,0,3,2] row_mask:0xf bank_mask:0xf bound_ctrl:1
	v_pk_mul_f32 v[92:93], v[60:61], v[64:65] op_sel_hi:[1,0]
	v_pk_fma_f32 v[92:93], v[0:1], v[44:45], v[92:93]
	v_add_f32_dpp v88, v88, v88 quad_perm:[2,3,0,1] row_mask:0xf bank_mask:0xf bound_ctrl:1
	v_pk_mul_f32 v[94:95], v[62:63], v[64:65] op_sel_hi:[1,0]
	v_pk_fma_f32 v[94:95], v[2:3], v[46:47], v[94:95]
	v_add_f32_dpp v88, v88, v88 row_half_mirror row_mask:0xf bank_mask:0xf bound_ctrl:1
	v_add_f32_e32 v81, v90, v91
	ds_read_b32 v40, v15 offset:19040
	v_add_f32_dpp v88, v88, v88 row_mirror row_mask:0xf bank_mask:0xf bound_ctrl:1
	v_pk_fma_f32 v[0:1], v[56:57], v[88:89], v[92:93] op_sel_hi:[1,0,1] neg_lo:[0,1,0] neg_hi:[0,1,0]
	v_pk_fma_f32 v[2:3], v[58:59], v[88:89], v[94:95] op_sel_hi:[1,0,1] neg_lo:[0,1,0] neg_hi:[0,1,0]
	v_cndmask_b32_e64 v114, v114, v88, s[64:65]
	ds_read_b128 v[44:47], v11 offset:20400
	ds_read_b128 v[48:51], v11 offset:20656
	ds_read_b128 v[52:55], v11 offset:20912
	ds_read_b128 v[56:59], v11 offset:21168
	ds_read_b128 v[60:63], v11 offset:21424
	s_waitcnt lgkmcnt(5)
; #define RW_WAIT(P, N) asm volatile("s_waitcnt lgkmcnt(" #N ")" : "+v"(P##w4), "+v"(P##kk4), "+v"(P##wr4), "+v"(P##ka4), "+v"(P##kp4), "+v"(P##v), "+v"(P##cc))
; #define RW_PAIR(ST) do { RW_LOAD(B, (ST) + 1); RW_WAIT(A, 7); RW_STEP(A, ST); RW_LOAD(A, (ST) + 2); RW_WAIT(B, 7); RW_STEP(B, (ST) + 1); } while (0)
; __device__ __forceinline__ void scans(int l, int s, unsigned char* shm) {
;     ...
;             RW_LOAD(A, 0);
;             RW_PAIR(0); RW_PAIR(2); RW_PAIR(4); RW_PAIR(6); RW_PAIR(8); RW_PAIR(10); RW_PAIR(12);
;             RW_LOAD(B, 15); RW_WAIT(A, 7); RW_STEP(A, 14); RW_WAIT(B, 0); RW_STEP(B, 15);
;     ...
;             ylw[(lane & 15) * 16 + loc] = ykeep;
	v_pk_mul_f32 v[84:85], v[0:1], v[24:25]
	v_pk_fma_f32 v[84:85], v[2:3], v[26:27], v[84:85]
	v_add_f32_e32 v86, v84, v85
	v_pk_mul_f32 v[90:91], v[0:1], v[28:29]
	v_pk_fma_f32 v[90:91], v[2:3], v[30:31], v[90:91]
	v_add_f32_dpp v88, v86, v86 quad_perm:[1,0,3,2] row_mask:0xf bank_mask:0xf bound_ctrl:1
	v_pk_mul_f32 v[92:93], v[36:37], v[40:41] op_sel_hi:[1,0]
	v_pk_fma_f32 v[92:93], v[0:1], v[20:21], v[92:93]
	v_add_f32_dpp v88, v88, v88 quad_perm:[2,3,0,1] row_mask:0xf bank_mask:0xf bound_ctrl:1
	v_pk_mul_f32 v[94:95], v[38:39], v[40:41] op_sel_hi:[1,0]
	v_pk_fma_f32 v[94:95], v[2:3], v[22:23], v[94:95]
	v_add_f32_dpp v88, v88, v88 row_half_mirror row_mask:0xf bank_mask:0xf bound_ctrl:1
	v_add_f32_e32 v82, v90, v91
	ds_read_b32 v64, v15 offset:20400
	v_add_f32_dpp v88, v88, v88 row_mirror row_mask:0xf bank_mask:0xf bound_ctrl:1
	v_pk_fma_f32 v[0:1], v[32:33], v[88:89], v[92:93] op_sel_hi:[1,0,1] neg_lo:[0,1,0] neg_hi:[0,1,0]
	v_pk_fma_f32 v[2:3], v[34:35], v[88:89], v[94:95] op_sel_hi:[1,0,1] neg_lo:[0,1,0] neg_hi:[0,1,0]
	v_cndmask_b32_e64 v114, v114, v88, s[66:67]
	s_waitcnt lgkmcnt(0)
	v_pk_mul_f32 v[84:85], v[0:1], v[48:49]
	v_pk_fma_f32 v[84:85], v[2:3], v[50:51], v[84:85]
	v_add_f32_e32 v86, v84, v85
	v_pk_mul_f32 v[90:91], v[0:1], v[52:53]
	v_pk_fma_f32 v[90:91], v[2:3], v[54:55], v[90:91]
	v_add_f32_dpp v88, v86, v86 quad_perm:[1,0,3,2] row_mask:0xf bank_mask:0xf bound_ctrl:1
	v_pk_mul_f32 v[92:93], v[60:61], v[64:65] op_sel_hi:[1,0]
	v_pk_fma_f32 v[92:93], v[0:1], v[44:45], v[92:93]
	v_add_f32_dpp v88, v88, v88 quad_perm:[2,3,0,1] row_mask:0xf bank_mask:0xf bound_ctrl:1
	v_pk_mul_f32 v[94:95], v[62:63], v[64:65] op_sel_hi:[1,0]
	v_pk_fma_f32 v[94:95], v[2:3], v[46:47], v[94:95]
	v_add_f32_dpp v88, v88, v88 row_half_mirror row_mask:0xf bank_mask:0xf bound_ctrl:1
	v_add_f32_e32 v83, v90, v91
	v_add_u32_e32 v112, v15, v125
	v_add_f32_dpp v88, v88, v88 row_mirror row_mask:0xf bank_mask:0xf bound_ctrl:1
	v_pk_fma_f32 v[0:1], v[56:57], v[88:89], v[92:93] op_sel_hi:[1,0,1] neg_lo:[0,1,0] neg_hi:[0,1,0]
	v_pk_fma_f32 v[2:3], v[58:59], v[88:89], v[94:95] op_sel_hi:[1,0,1] neg_lo:[0,1,0] neg_hi:[0,1,0]
	v_cndmask_b32_e64 v114, v114, v88, s[68:69]
	v_add_u32_e32 v113, v16, v125
	ds_read_b32 v110, v112
	ds_read_b64 v[116:117], v113
	v_and_b32_e32 v118, 1, v4
	v_cmp_ne_u32_e32 vcc, 0, v118
	v_add_f32_dpp v68, v68, v68 row_ror:8 row_mask:0xf bank_mask:0x3
	v_add_f32_dpp v68, v76, v76 row_ror:8 row_mask:0xf bank_mask:0xc
	v_add_f32_dpp v69, v69, v69 row_ror:8 row_mask:0xf bank_mask:0x3
	v_add_f32_dpp v69, v77, v77 row_ror:8 row_mask:0xf bank_mask:0xc
	v_add_f32_dpp v70, v70, v70 row_ror:8 row_mask:0xf bank_mask:0x3
	v_add_f32_dpp v70, v78, v78 row_ror:8 row_mask:0xf bank_mask:0xc
	v_add_f32_dpp v71, v71, v71 row_ror:8 row_mask:0xf bank_mask:0x3
	v_add_f32_dpp v71, v79, v79 row_ror:8 row_mask:0xf bank_mask:0xc
	v_add_f32_dpp v72, v72, v72 row_ror:8 row_mask:0xf bank_mask:0x3
	v_add_f32_dpp v72, v80, v80 row_ror:8 row_mask:0xf bank_mask:0xc
	v_add_f32_dpp v73, v73, v73 row_ror:8 row_mask:0xf bank_mask:0x3
	v_add_f32_dpp v73, v81, v81 row_ror:8 row_mask:0xf bank_mask:0xc
	v_add_f32_dpp v74, v74, v74 row_ror:8 row_mask:0xf bank_mask:0x3
	v_add_f32_dpp v74, v82, v82 row_ror:8 row_mask:0xf bank_mask:0xc
	v_add_f32_dpp v75, v75, v75 row_ror:8 row_mask:0xf bank_mask:0x3
	v_add_f32_dpp v75, v83, v83 row_ror:8 row_mask:0xf bank_mask:0xc
	v_add_f32_dpp v68, v68, v68 row_half_mirror row_mask:0xf bank_mask:0x5
	v_add_f32_dpp v68, v72, v72 row_half_mirror row_mask:0xf bank_mask:0xa
	v_add_f32_dpp v69, v69, v69 row_half_mirror row_mask:0xf bank_mask:0x5
	v_add_f32_dpp v69, v73, v73 row_half_mirror row_mask:0xf bank_mask:0xa
	v_add_f32_dpp v70, v70, v70 row_half_mirror row_mask:0xf bank_mask:0x5
	v_add_f32_dpp v70, v74, v74 row_half_mirror row_mask:0xf bank_mask:0xa
	v_add_f32_dpp v71, v71, v71 row_half_mirror row_mask:0xf bank_mask:0x5
	v_add_f32_dpp v71, v75, v75 row_half_mirror row_mask:0xf bank_mask:0xa
	v_cndmask_b32_e64 v100, v70, v68, s[100:101]
	v_cndmask_b32_e64 v101, v71, v69, s[100:101]
	v_cndmask_b32_e64 v102, v68, v70, s[100:101]
	v_cndmask_b32_e64 v103, v69, v71, s[100:101]
	v_add_f32_dpp v104, v100, v102 quad_perm:[2,3,0,1] row_mask:0xf bank_mask:0xf bound_ctrl:1
	v_add_f32_dpp v105, v101, v103 quad_perm:[2,3,0,1] row_mask:0xf bank_mask:0xf bound_ctrl:1
	v_lshl_add_u32 v17, s20, 10, v14
	v_cndmask_b32_e32 v106, v105, v104, vcc
	v_cndmask_b32_e32 v107, v104, v105, vcc
	s_add_i32 s16, s16, 1
	s_addk_i32 s17, 0x100
	v_add_u32_e32 v10, 16, v10
	v_add_f32_dpp v108, v106, v107 quad_perm:[1,0,3,2] row_mask:0xf bank_mask:0xf bound_ctrl:1
	s_waitcnt lgkmcnt(0)
	v_fmac_f32_e32 v108, v110, v117
	v_fma_f32 v108, -v116, v114, v108
	ds_write_b32 v17, v108 offset:43520
	s_cmpk_eq_i32 s17, 0x7f00
	s_waitcnt lgkmcnt(0)
	s_barrier
	s_cbranch_scc1 .LBB0_761
